# stack of the small edits: conversion item waits, rotary table prefetch, rotary scalar f32 ops, in-proj column swap on odd rounds, conv phase reverse walk
# baseline (speedup 1.0000x reference)
.LBB0_151:
	s_andn2_b64 vcc, exec, s[0:1]
	s_cbranch_vccnz .LBB0_153
	s_lshr_b32 s0, s75, 3
	s_mulk_i32 s0, 0x880
	s_lshl_b32 s1, s75, 8
	s_and_b32 s1, s1, 0x700
	s_add_i32 s0, s0, s66
	s_add_i32 s0, s0, s1
	v_or_b32_e32 v152, s0, v176
	s_lshl_b32 s0, s69, 8
	v_lshl_or_b32 v0, v175, 3, s0
	v_or_b32_e32 v154, s61, v0
	s_nop 0
	v_and_b32_e32 v0, 0x7e, v154
	v_lshlrev_b32_e32 v0, 2, v0
	v_lshl_add_u64 v[170:171], s[42:43], 0, v[0:1]
	v_mul_hi_i32 v0, v152, s63
	v_lshrrev_b32_e32 v130, 31, v0
	v_ashrrev_i32_e32 v0, 10, v0
	v_add_u32_e32 v0, v0, v130
	v_mul_i32_i24_e32 v0, 0x880, v0
	v_sub_u32_e32 v166, v152, v0
	v_ashrrev_i32_e32 v167, 31, v166
	v_lshlrev_b64 v[130:131], 9, v[166:167]
	v_add_u32_e32 v153, 16, v152
	v_lshl_add_u64 v[130:131], v[170:171], 0, v[130:131]
	v_mul_hi_i32 v0, v153, s63
	global_load_dwordx4 v[178:181], v[130:131], off offset:16
	global_load_dwordx4 v[182:185], v[130:131], off
	v_lshrrev_b32_e32 v130, 31, v0
	v_ashrrev_i32_e32 v0, 10, v0
	v_add_u32_e32 v0, v0, v130
	v_mul_i32_i24_e32 v0, 0x880, v0
	v_sub_u32_e32 v198, v153, v0
	v_ashrrev_i32_e32 v199, 31, v198
	v_lshlrev_b64 v[130:131], 9, v[198:199]
	v_add_u32_e32 v177, 32, v152
	v_lshl_add_u64 v[130:131], v[170:171], 0, v[130:131]
	v_mul_hi_i32 v0, v177, s63
	global_load_dwordx4 v[186:189], v[130:131], off offset:16
	global_load_dwordx4 v[190:193], v[130:131], off
	v_lshrrev_b32_e32 v130, 31, v0
	v_ashrrev_i32_e32 v0, 10, v0
	v_add_u32_e32 v0, v0, v130
	v_mul_i32_i24_e32 v0, 0x880, v0
	v_sub_u32_e32 v200, v177, v0
	v_ashrrev_i32_e32 v201, 31, v200
	v_lshlrev_b64 v[130:131], 9, v[200:201]
	v_add_u32_e32 v201, 48, v152
	v_lshl_add_u64 v[130:131], v[170:171], 0, v[130:131]
	v_mul_hi_i32 v0, v201, s63
	global_load_dwordx4 v[138:141], v[130:131], off offset:16
	global_load_dwordx4 v[142:145], v[130:131], off
	v_lshrrev_b32_e32 v130, 31, v0
	v_ashrrev_i32_e32 v0, 10, v0
	v_add_u32_e32 v0, v0, v130
	v_mul_i32_i24_e32 v0, 0x880, v0
	v_sub_u32_e32 v172, v201, v0
	v_ashrrev_i32_e32 v173, 31, v172
	v_lshlrev_b64 v[130:131], 9, v[172:173]
	v_lshl_add_u64 v[134:135], v[170:171], 0, v[130:131]
	global_load_dwordx4 v[130:133], v[134:135], off offset:16
	s_nop 0
	global_load_dwordx4 v[134:137], v[134:135], off
	s_waitcnt vmcnt(0)
	v_mul_f32_e32 v204, v122, v179
	v_mul_f32_e32 v205, v123, v179
	v_cmp_lt_i32_e32 vcc, s11, v166
	v_fma_f32 v206, v122, v178, -v205
	v_fma_f32 v205, v123, v178, v204
	v_mul_f32_e32 v166, v126, v183
	v_mul_f32_e32 v167, v127, v183
	v_mov_b32_e32 v204, v181
	v_mul_f32_e32 v208, v124, v204
	v_mul_f32_e32 v209, v125, v204
	v_fma_f32 v168, v126, v182, -v167
	v_fma_f32 v167, v127, v182, v166
	v_mov_b32_e32 v202, v185
	v_fma_f32 v212, v124, v180, -v209
	v_fma_f32 v209, v125, v180, v208
	v_cndmask_b32_e32 v0, 0, v231, vcc
	v_mul_f32_e32 v194, v128, v202
	v_mul_f32_e32 v195, v129, v202
	v_mov_b32_e32 v169, v167
	v_mov_b32_e32 v213, v209
	s_movk_i32 s0, 0x1bff
	v_fma_f32 v196, v128, v184, -v195
	v_fma_f32 v195, v129, v184, v194
	v_mul_f32_e32 v216, v0, v168
	v_mul_f32_e32 v217, v0, v169
	v_mov_b32_e32 v207, v205
	v_mul_f32_e32 v222, v0, v212
	v_mul_f32_e32 v223, v0, v213
	v_cmp_lt_i32_e64 s[0:1], s0, v154
	v_mov_b32_e32 v197, v195
	v_mul_f32_e32 v220, v0, v206
	v_mul_f32_e32 v221, v0, v207
	v_cndmask_b32_e64 v155, v209, v223, s[0:1]
	v_cndmask_b32_e64 v166, v212, v222, s[0:1]
	v_cndmask_b32_e64 v167, v167, v217, s[0:1]
	v_cndmask_b32_e64 v168, v168, v216, s[0:1]
	v_mul_f32_e32 v218, v0, v196
	v_mul_f32_e32 v219, v0, v197
	v_cndmask_b32_e64 v169, v205, v221, s[0:1]
	v_cndmask_b32_e64 v173, v206, v220, s[0:1]
	v_cvt_pk_bf16_f32 v194, v168, v167
	v_cvt_pk_bf16_f32 v197, v166, v155
	v_mov_b64_e32 v[166:167], s[8:9]
	v_ashrrev_i32_e32 v155, 31, v154
	v_cndmask_b32_e64 v181, v195, v219, s[0:1]
	v_cndmask_b32_e64 v185, v196, v218, s[0:1]
	v_cvt_pk_bf16_f32 v196, v173, v169
	v_mad_i64_i32 v[206:207], s[6:7], v152, s47, v[166:167]
	v_lshlrev_b64 v[168:169], 1, v[154:155]
	v_cvt_pk_bf16_f32 v195, v185, v181
	v_lshl_add_u64 v[206:207], v[206:207], 0, v[168:169]
	global_store_dwordx4 v[206:207], v[194:197], off
	s_nop 1
	v_mul_f32_e32 v194, v118, v183
	v_mul_f32_e32 v195, v119, v183
	s_movk_i32 s6, 0x1b7f
	v_fma_f32 v196, v118, v182, -v195
	v_fma_f32 v183, v119, v182, v194
	v_mul_f32_e32 v194, v120, v202
	v_mul_f32_e32 v195, v121, v202
	v_mov_b32_e32 v197, v183
	v_fma_f32 v202, v120, v184, -v195
	v_fma_f32 v185, v121, v184, v194
	v_mul_f32_e32 v194, v110, v179
	v_mul_f32_e32 v195, v111, v179
	v_mov_b32_e32 v203, v185
	v_fma_f32 v208, v110, v178, -v195
	v_fma_f32 v179, v111, v178, v194
	v_mul_f32_e32 v194, v112, v204
	v_mul_f32_e32 v195, v113, v204
	v_mov_b32_e32 v209, v179
	v_fma_f32 v204, v112, v180, -v195
	v_fma_f32 v181, v113, v180, v194
	v_cmp_lt_i32_e32 vcc, s6, v154
	v_mov_b32_e32 v205, v181
	v_mul_f32_e32 v154, v0, v196
	v_mul_f32_e32 v155, v0, v197
	v_mul_f32_e32 v194, v0, v202
	v_mul_f32_e32 v195, v0, v203
	v_mul_f32_e32 v212, v0, v208
	v_mul_f32_e32 v213, v0, v209
	v_mul_f32_e32 v216, v0, v204
	v_mul_f32_e32 v217, v0, v205
	v_cndmask_b32_e32 v0, v181, v217, vcc
	v_cndmask_b32_e32 v173, v204, v216, vcc
	v_cndmask_b32_e32 v180, v179, v213, vcc
	v_cndmask_b32_e32 v181, v208, v212, vcc
	v_cndmask_b32_e32 v179, v185, v195, vcc
	v_cndmask_b32_e32 v182, v202, v194, vcc
	v_cndmask_b32_e32 v155, v183, v155, vcc
	v_cndmask_b32_e32 v154, v196, v154, vcc
	v_cvt_pk_bf16_f32 v178, v154, v155
	v_cvt_pk_bf16_f32 v179, v182, v179
	v_cvt_pk_bf16_f32 v180, v181, v180
	v_cvt_pk_bf16_f32 v181, v173, v0
	global_store_dwordx4 v[206:207], v[178:181], off offset:256
	v_mul_f32_e32 v154, v114, v191
	v_mul_f32_e32 v155, v115, v191
	v_mul_f32_e32 v184, v106, v187
	v_mul_f32_e32 v185, v107, v187
	v_fma_f32 v178, v114, v190, -v155
	v_fma_f32 v155, v115, v190, v154
	v_fma_f32 v194, v106, v186, -v185
	v_fma_f32 v185, v107, v186, v184
	v_mov_b32_e32 v154, v193
	v_mov_b32_e32 v184, v189
	v_mul_f32_e32 v180, v116, v154
	v_mul_f32_e32 v181, v117, v154
	v_mul_f32_e32 v196, v108, v184
	v_mul_f32_e32 v197, v109, v184
	v_cmp_lt_i32_e64 s[38:39], s11, v198
	v_fma_f32 v182, v116, v192, -v181
	v_fma_f32 v181, v117, v192, v180
	v_fma_f32 v198, v108, v188, -v197
	v_fma_f32 v197, v109, v188, v196
	v_cndmask_b32_e64 v0, 0, v231, s[38:39]
	v_mov_b32_e32 v183, v181
	v_mov_b32_e32 v199, v197
	v_mov_b32_e32 v179, v155
	v_mul_f32_e32 v204, v0, v182
	v_mul_f32_e32 v205, v0, v183
	v_mov_b32_e32 v195, v185
	v_mul_f32_e32 v208, v0, v198
	v_mul_f32_e32 v209, v0, v199
	v_mul_f32_e32 v202, v0, v178
	v_mul_f32_e32 v203, v0, v179
	v_mul_f32_e32 v206, v0, v194
	v_mul_f32_e32 v207, v0, v195
	v_cndmask_b32_e64 v173, v197, v209, s[0:1]
	v_cndmask_b32_e64 v183, v198, v208, s[0:1]
	v_cndmask_b32_e64 v179, v181, v205, s[0:1]
	v_cndmask_b32_e64 v181, v182, v204, s[0:1]
	v_cndmask_b32_e64 v180, v185, v207, s[0:1]
	v_cndmask_b32_e64 v185, v194, v206, s[0:1]
	v_cndmask_b32_e64 v155, v155, v203, s[0:1]
	v_cndmask_b32_e64 v178, v178, v202, s[0:1]
	v_cvt_pk_bf16_f32 v179, v181, v179
	v_cvt_pk_bf16_f32 v181, v183, v173
	v_mad_i64_i32 v[182:183], s[6:7], v153, s47, v[166:167]
	v_cvt_pk_bf16_f32 v178, v178, v155
	v_cvt_pk_bf16_f32 v180, v185, v180
	v_lshl_add_u64 v[182:183], v[182:183], 0, v[168:169]
	global_store_dwordx4 v[182:183], v[178:181], off
	s_nop 1
	v_mul_f32_e32 v178, v102, v191
	v_mul_f32_e32 v179, v103, v191
	v_mul_f32_e32 v155, v105, v154
	v_mul_f32_e32 v154, v104, v154
	v_fma_f32 v180, v102, v190, -v179
	v_fma_f32 v179, v103, v190, v178
	v_fma_f32 v190, v104, v192, -v155
	v_fma_f32 v155, v105, v192, v154
	v_mul_f32_e32 v192, v94, v187
	v_mul_f32_e32 v193, v95, v187
	v_mul_f32_e32 v185, v97, v184
	v_mul_f32_e32 v184, v96, v184
	v_fma_f32 v194, v94, v186, -v193
	v_fma_f32 v187, v95, v186, v192
	v_fma_f32 v192, v96, v188, -v185
	v_fma_f32 v185, v97, v188, v184
	v_mov_b32_e32 v181, v179
	v_mov_b32_e32 v191, v155
	v_mov_b32_e32 v195, v187
	v_mov_b32_e32 v193, v185
	v_mul_f32_e32 v188, v0, v180
	v_mul_f32_e32 v189, v0, v181
	v_mul_f32_e32 v196, v0, v190
	v_mul_f32_e32 v197, v0, v191
	v_mul_f32_e32 v198, v0, v194
	v_mul_f32_e32 v199, v0, v195
	v_mul_f32_e32 v202, v0, v192
	v_mul_f32_e32 v203, v0, v193
	v_cndmask_b32_e32 v0, v185, v203, vcc
	v_cndmask_b32_e32 v153, v192, v202, vcc
	v_cndmask_b32_e32 v154, v187, v199, vcc
	v_cndmask_b32_e32 v173, v194, v198, vcc
	v_cndmask_b32_e32 v155, v155, v197, vcc
	v_cndmask_b32_e32 v181, v190, v196, vcc
	v_cndmask_b32_e32 v178, v179, v189, vcc
	v_cndmask_b32_e32 v179, v180, v188, vcc
	v_cvt_pk_bf16_f32 v178, v179, v178
	v_cvt_pk_bf16_f32 v179, v181, v155
	v_cvt_pk_bf16_f32 v180, v173, v154
	v_cvt_pk_bf16_f32 v181, v153, v0
	global_store_dwordx4 v[182:183], v[178:181], off offset:256
	s_nop 1
	v_add_u32_e32 v147, 0x80, v152
	v_mul_hi_i32 v0, v147, s63
	v_lshrrev_b32_e32 v94, 31, v0
	v_ashrrev_i32_e32 v0, 10, v0
	v_add_u32_e32 v0, v0, v94
	v_mul_i32_i24_e32 v0, 0x880, v0
	v_sub_u32_e32 v224, v147, v0
	v_ashrrev_i32_e32 v225, 31, v224
	v_lshlrev_b64 v[94:95], 9, v[224:225]
	v_add_u32_e32 v176, 0x90, v152
	v_lshl_add_u64 v[94:95], v[170:171], 0, v[94:95]
	v_mul_hi_i32 v0, v176, s63
	global_load_dwordx4 v[114:117], v[94:95], off offset:16
	global_load_dwordx4 v[118:121], v[94:95], off
	v_lshrrev_b32_e32 v94, 31, v0
	v_ashrrev_i32_e32 v0, 10, v0
	v_add_u32_e32 v0, v0, v94
	v_mul_i32_i24_e32 v0, 0x880, v0
	v_sub_u32_e32 v228, v176, v0
	v_ashrrev_i32_e32 v229, 31, v228
	v_lshlrev_b64 v[94:95], 9, v[228:229]
	v_add_u32_e32 v233, 0xa0, v152
	v_lshl_add_u64 v[94:95], v[170:171], 0, v[94:95]
	v_mul_hi_i32 v0, v233, s63
	global_load_dwordx4 v[122:125], v[94:95], off offset:16
	global_load_dwordx4 v[126:129], v[94:95], off
	v_lshrrev_b32_e32 v94, 31, v0
	v_ashrrev_i32_e32 v0, 10, v0
	v_add_u32_e32 v0, v0, v94
	v_mul_i32_i24_e32 v0, 0x880, v0
	v_sub_u32_e32 v238, v233, v0
	v_ashrrev_i32_e32 v239, 31, v238
	v_lshlrev_b64 v[94:95], 9, v[238:239]
	v_add_u32_e32 v252, 0xb0, v152
	v_lshl_add_u64 v[94:95], v[170:171], 0, v[94:95]
	v_mul_hi_i32 v0, v252, s63
	global_load_dwordx4 v[106:109], v[94:95], off offset:16
	global_load_dwordx4 v[110:113], v[94:95], off
	v_lshrrev_b32_e32 v94, 31, v0
	v_ashrrev_i32_e32 v0, 10, v0
	v_add_u32_e32 v0, v0, v94
	v_mul_i32_i24_e32 v0, 0x880, v0
	v_sub_u32_e32 v226, v252, v0
	v_ashrrev_i32_e32 v227, 31, v226
	v_lshlrev_b64 v[94:95], 9, v[226:227]
	v_lshl_add_u64 v[102:103], v[170:171], 0, v[94:95]
	global_load_dwordx4 v[94:97], v[102:103], off offset:16
	s_nop 0
	global_load_dwordx4 v[102:105], v[102:103], off
	v_mul_f32_e32 v154, v98, v143
	v_mul_f32_e32 v155, v99, v143
	v_mul_f32_e32 v184, v90, v139
	v_mul_f32_e32 v185, v91, v139
	v_fma_f32 v178, v98, v142, -v155
	v_fma_f32 v155, v99, v142, v154
	v_fma_f32 v186, v90, v138, -v185
	v_fma_f32 v185, v91, v138, v184
	v_mov_b32_e32 v154, v145
	v_mov_b32_e32 v184, v141
	v_mul_f32_e32 v180, v100, v154
	v_mul_f32_e32 v181, v101, v154
	v_mul_f32_e32 v188, v92, v184
	v_mul_f32_e32 v189, v93, v184
	v_cmp_lt_i32_e64 s[38:39], s11, v200
	v_fma_f32 v182, v100, v144, -v181
	v_fma_f32 v181, v101, v144, v180
	v_fma_f32 v190, v92, v140, -v189
	v_fma_f32 v189, v93, v140, v188
	v_cndmask_b32_e64 v0, 0, v231, s[38:39]
	v_mov_b32_e32 v179, v155
	v_mov_b32_e32 v183, v181
	v_mov_b32_e32 v187, v185
	v_mov_b32_e32 v191, v189
	v_mul_f32_e32 v192, v0, v178
	v_mul_f32_e32 v193, v0, v179
	v_mul_f32_e32 v194, v0, v182
	v_mul_f32_e32 v195, v0, v183
	v_mul_f32_e32 v196, v0, v186
	v_mul_f32_e32 v197, v0, v187
	v_mul_f32_e32 v198, v0, v190
	v_mul_f32_e32 v199, v0, v191
	v_cndmask_b32_e64 v141, v189, v199, s[0:1]
	v_cndmask_b32_e64 v145, v190, v198, s[0:1]
	v_cndmask_b32_e64 v153, v185, v197, s[0:1]
	v_cndmask_b32_e64 v173, v186, v196, s[0:1]
	v_cndmask_b32_e64 v179, v181, v195, s[0:1]
	v_cndmask_b32_e64 v180, v182, v194, s[0:1]
	v_cndmask_b32_e64 v155, v155, v193, s[0:1]
	v_cndmask_b32_e64 v178, v178, v192, s[0:1]
	v_mad_i64_i32 v[182:183], s[6:7], v177, s47, v[166:167]
	v_cvt_pk_bf16_f32 v178, v178, v155
	v_cvt_pk_bf16_f32 v179, v180, v179
	v_cvt_pk_bf16_f32 v180, v173, v153
	v_cvt_pk_bf16_f32 v181, v145, v141
	v_lshl_add_u64 v[182:183], v[182:183], 0, v[168:169]
	global_store_dwordx4 v[182:183], v[178:181], off
	s_nop 1
	v_mul_f32_e32 v178, v86, v143
	v_mul_f32_e32 v179, v87, v143
	v_mul_f32_e32 v155, v89, v154
	v_mul_f32_e32 v154, v88, v154
	v_fma_f32 v180, v86, v142, -v179
	v_fma_f32 v143, v87, v142, v178
	v_fma_f32 v178, v88, v144, -v155
	v_fma_f32 v145, v89, v144, v154
	v_mul_f32_e32 v154, v78, v139
	v_mul_f32_e32 v155, v79, v139
	v_mov_b32_e32 v181, v143
	v_fma_f32 v186, v78, v138, -v155
	v_fma_f32 v139, v79, v138, v154
	v_mul_f32_e32 v154, v80, v184
	v_mul_f32_e32 v155, v81, v184
	v_mov_b32_e32 v179, v145
	v_fma_f32 v184, v80, v140, -v155
	v_fma_f32 v141, v81, v140, v154
	v_mov_b32_e32 v187, v139
	v_mov_b32_e32 v185, v141
	v_mul_f32_e32 v154, v0, v180
	v_mul_f32_e32 v155, v0, v181
	v_mul_f32_e32 v188, v0, v178
	v_mul_f32_e32 v189, v0, v179
	v_mul_f32_e32 v190, v0, v186
	v_mul_f32_e32 v191, v0, v187
	v_mul_f32_e32 v192, v0, v184
	v_mul_f32_e32 v193, v0, v185
	v_cndmask_b32_e32 v0, v141, v193, vcc
	v_cndmask_b32_e32 v141, v184, v192, vcc
	v_cndmask_b32_e32 v140, v139, v191, vcc
	v_cndmask_b32_e32 v142, v186, v190, vcc
	v_cndmask_b32_e32 v139, v145, v189, vcc
	v_cndmask_b32_e32 v144, v178, v188, vcc
	v_cndmask_b32_e32 v138, v143, v155, vcc
	v_cndmask_b32_e32 v143, v180, v154, vcc
	v_cvt_pk_bf16_f32 v138, v143, v138
	v_cvt_pk_bf16_f32 v139, v144, v139
	v_cvt_pk_bf16_f32 v140, v142, v140
	v_cvt_pk_bf16_f32 v141, v141, v0
	global_store_dwordx4 v[182:183], v[138:141], off offset:256
	v_mov_b32_e32 v142, v137
	v_mul_f32_e32 v144, v84, v142
	v_mul_f32_e32 v145, v85, v142
	v_cmp_lt_i32_e64 s[38:39], s11, v172
	v_fma_f32 v154, v84, v136, -v145
	v_fma_f32 v145, v85, v136, v144
	v_mul_f32_e32 v138, v82, v135
	v_mul_f32_e32 v139, v83, v135
	v_mov_b32_e32 v144, v133
	v_mul_f32_e32 v172, v74, v131
	v_mul_f32_e32 v173, v75, v131
	v_mul_f32_e32 v180, v76, v144
	v_mul_f32_e32 v181, v77, v144
	v_fma_f32 v140, v82, v134, -v139
	v_fma_f32 v139, v83, v134, v138
	v_fma_f32 v178, v74, v130, -v173
	v_fma_f32 v173, v75, v130, v172
	v_fma_f32 v182, v76, v132, -v181
	v_fma_f32 v181, v77, v132, v180
	v_cndmask_b32_e64 v0, 0, v231, s[38:39]
	v_mov_b32_e32 v141, v139
	v_mov_b32_e32 v155, v145
	v_mov_b32_e32 v179, v173
	v_mov_b32_e32 v183, v181
	v_mul_f32_e32 v184, v0, v140
	v_mul_f32_e32 v185, v0, v141
	v_mul_f32_e32 v186, v0, v154
	v_mul_f32_e32 v187, v0, v155
	v_mul_f32_e32 v188, v0, v178
	v_mul_f32_e32 v189, v0, v179
	v_mul_f32_e32 v190, v0, v182
	v_mul_f32_e32 v191, v0, v183
	v_cndmask_b32_e64 v133, v181, v191, s[0:1]
	v_cndmask_b32_e64 v137, v182, v190, s[0:1]
	v_cndmask_b32_e64 v141, v173, v189, s[0:1]
	v_cndmask_b32_e64 v143, v178, v188, s[0:1]
	v_cndmask_b32_e64 v145, v145, v187, s[0:1]
	v_cndmask_b32_e64 v153, v154, v186, s[0:1]
	v_cndmask_b32_e64 v138, v139, v185, s[0:1]
	v_cndmask_b32_e64 v139, v140, v184, s[0:1]
	v_mad_i64_i32 v[154:155], s[6:7], v201, s47, v[166:167]
	v_cvt_pk_bf16_f32 v138, v139, v138
	v_cvt_pk_bf16_f32 v139, v153, v145
	v_cvt_pk_bf16_f32 v140, v143, v141
	v_cvt_pk_bf16_f32 v141, v137, v133
	v_lshl_add_u64 v[154:155], v[154:155], 0, v[168:169]
	global_store_dwordx4 v[154:155], v[138:141], off
	s_nop 1
	v_mul_f32_e32 v138, v70, v135
	v_mul_f32_e32 v139, v71, v135
	s_nop 0
	v_fma_f32 v140, v70, v134, -v139
	v_fma_f32 v135, v71, v134, v138
	v_mul_f32_e32 v138, v72, v142
	v_mul_f32_e32 v139, v73, v142
	v_mov_b32_e32 v141, v135
	v_fma_f32 v142, v72, v136, -v139
	v_fma_f32 v137, v73, v136, v138
	v_mul_f32_e32 v138, v66, v131
	v_mul_f32_e32 v139, v67, v131
	v_mov_b32_e32 v143, v137
	v_fma_f32 v172, v66, v130, -v139
	v_fma_f32 v131, v67, v130, v138
	v_mul_f32_e32 v138, v68, v144
	v_mul_f32_e32 v139, v69, v144
	v_mov_b32_e32 v173, v131
	v_fma_f32 v144, v68, v132, -v139
	v_fma_f32 v133, v69, v132, v138
	v_mul_f32_e32 v138, v0, v140
	v_mul_f32_e32 v139, v0, v141
	v_mov_b32_e32 v145, v133
	v_mul_f32_e32 v178, v0, v142
	v_mul_f32_e32 v179, v0, v143
	v_mul_f32_e32 v180, v0, v172
	v_mul_f32_e32 v181, v0, v173
	v_mul_f32_e32 v182, v0, v144
	v_mul_f32_e32 v183, v0, v145
	v_cndmask_b32_e32 v0, v133, v183, vcc
	v_cndmask_b32_e32 v133, v144, v182, vcc
	v_cndmask_b32_e32 v132, v131, v181, vcc
	v_cndmask_b32_e32 v134, v172, v180, vcc
	v_cndmask_b32_e32 v131, v137, v179, vcc
	v_cndmask_b32_e32 v136, v142, v178, vcc
	v_cndmask_b32_e32 v130, v135, v139, vcc
	v_cndmask_b32_e32 v135, v140, v138, vcc
	v_cvt_pk_bf16_f32 v130, v135, v130
	v_cvt_pk_bf16_f32 v131, v136, v131
	v_cvt_pk_bf16_f32 v132, v134, v132
	v_cvt_pk_bf16_f32 v133, v133, v0
	global_store_dwordx4 v[154:155], v[130:133], off offset:256
	s_waitcnt vmcnt(4)
	v_mov_b32_e32 v170, v121
	v_mul_f32_e32 v198, v64, v170
	v_mul_f32_e32 v199, v65, v170
	v_mul_f32_e32 v152, v62, v119
	v_mul_f32_e32 v153, v63, v119
	v_fma_f32 v200, v64, v120, -v199
	v_fma_f32 v199, v65, v120, v198
	v_mul_f32_e32 v202, v58, v115
	v_mul_f32_e32 v203, v59, v115
	v_mov_b32_e32 v198, v117
	v_mul_f32_e32 v206, v60, v198
	v_mul_f32_e32 v207, v61, v198
	v_cmp_lt_i32_e64 s[38:39], s11, v224
	v_fma_f32 v154, v62, v118, -v153
	v_fma_f32 v153, v63, v118, v152
	v_fma_f32 v204, v58, v114, -v203
	v_fma_f32 v203, v59, v114, v202
	v_fma_f32 v208, v60, v116, -v207
	v_fma_f32 v207, v61, v116, v206
	v_cndmask_b32_e64 v0, 0, v231, s[38:39]
	v_mov_b32_e32 v155, v153
	v_mov_b32_e32 v201, v199
	v_mov_b32_e32 v205, v203
	v_mov_b32_e32 v209, v207
	v_mul_f32_e32 v212, v0, v154
	v_mul_f32_e32 v213, v0, v155
	v_mul_f32_e32 v216, v0, v200
	v_mul_f32_e32 v217, v0, v201
	v_mul_f32_e32 v218, v0, v204
	v_mul_f32_e32 v219, v0, v205
	v_mul_f32_e32 v220, v0, v208
	v_mul_f32_e32 v221, v0, v209
	v_cndmask_b32_e64 v155, v207, v221, s[0:1]
	v_cndmask_b32_e64 v171, v208, v220, s[0:1]
	v_cndmask_b32_e64 v173, v203, v219, s[0:1]
	v_cndmask_b32_e64 v181, v204, v218, s[0:1]
	v_cndmask_b32_e64 v185, v199, v217, s[0:1]
	v_cndmask_b32_e64 v195, v200, v216, s[0:1]
	v_cndmask_b32_e64 v152, v153, v213, s[0:1]
	v_cndmask_b32_e64 v153, v154, v212, s[0:1]
	v_mad_i64_i32 v[200:201], s[6:7], v147, s47, v[166:167]
	v_cvt_pk_bf16_f32 v152, v153, v152
	v_cvt_pk_bf16_f32 v153, v195, v185
	v_cvt_pk_bf16_f32 v154, v181, v173
	v_cvt_pk_bf16_f32 v155, v171, v155
	v_lshl_add_u64 v[200:201], v[200:201], 0, v[168:169]
	global_store_dwordx4 v[200:201], v[152:155], off
	s_nop 1
	v_mul_f32_e32 v152, v54, v119
	v_mul_f32_e32 v153, v55, v119
	v_mul_f32_e32 v171, v57, v170
	v_mul_f32_e32 v170, v56, v170
	v_fma_f32 v154, v54, v118, -v153
	v_fma_f32 v153, v55, v118, v152
	v_fma_f32 v182, v56, v120, -v171
	v_fma_f32 v171, v57, v120, v170
	v_mul_f32_e32 v184, v46, v115
	v_mul_f32_e32 v185, v47, v115
	v_mov_b32_e32 v155, v153
	v_fma_f32 v202, v46, v114, -v185
	v_fma_f32 v179, v47, v114, v184
	v_mul_f32_e32 v184, v48, v198
	v_mul_f32_e32 v185, v49, v198
	v_mov_b32_e32 v183, v171
	v_fma_f32 v198, v48, v116, -v185
	v_fma_f32 v181, v49, v116, v184
	v_mov_b32_e32 v203, v179
	v_mov_b32_e32 v199, v181
	v_mul_f32_e32 v184, v0, v154
	v_mul_f32_e32 v185, v0, v155
	v_mul_f32_e32 v204, v0, v182
	v_mul_f32_e32 v205, v0, v183
	v_mul_f32_e32 v206, v0, v202
	v_mul_f32_e32 v207, v0, v203
	v_mul_f32_e32 v208, v0, v198
	v_mul_f32_e32 v209, v0, v199
	v_cndmask_b32_e32 v0, v181, v209, vcc
	v_cndmask_b32_e32 v155, v198, v208, vcc
	v_cndmask_b32_e32 v170, v179, v207, vcc
	v_cndmask_b32_e32 v173, v202, v206, vcc
	v_cndmask_b32_e32 v171, v171, v205, vcc
	v_cndmask_b32_e32 v177, v182, v204, vcc
	v_cndmask_b32_e32 v152, v153, v185, vcc
	v_cndmask_b32_e32 v153, v154, v184, vcc
	v_cvt_pk_bf16_f32 v152, v153, v152
	v_cvt_pk_bf16_f32 v153, v177, v171
	v_cvt_pk_bf16_f32 v154, v173, v170
	v_cvt_pk_bf16_f32 v155, v155, v0
	global_store_dwordx4 v[200:201], v[152:155], off offset:256
	v_mov_b32_e32 v170, v129
	v_mul_f32_e32 v178, v52, v170
	v_mul_f32_e32 v179, v53, v170
	v_mul_f32_e32 v152, v50, v127
	v_mul_f32_e32 v153, v51, v127
	v_fma_f32 v180, v52, v128, -v179
	v_fma_f32 v179, v53, v128, v178
	v_cmp_lt_i32_e64 s[38:39], s11, v228
	v_mov_b32_e32 v178, v125
	v_fma_f32 v154, v50, v126, -v153
	v_fma_f32 v153, v51, v126, v152
	v_mul_f32_e32 v182, v42, v123
	v_mul_f32_e32 v183, v43, v123
	v_mul_f32_e32 v194, v44, v178
	v_mul_f32_e32 v195, v45, v178
	v_cndmask_b32_e64 v0, 0, v231, s[38:39]
	v_fma_f32 v184, v42, v122, -v183
	v_fma_f32 v183, v43, v122, v182
	v_fma_f32 v198, v44, v124, -v195
	v_fma_f32 v195, v45, v124, v194
	v_mov_b32_e32 v155, v153
	v_mov_b32_e32 v181, v179
	v_mul_f32_e32 v200, v0, v154
	v_mul_f32_e32 v201, v0, v155
	v_mul_f32_e32 v202, v0, v180
	v_mul_f32_e32 v203, v0, v181
	v_mov_b32_e32 v185, v183
	v_mov_b32_e32 v199, v195
	v_mul_f32_e32 v204, v0, v184
	v_mul_f32_e32 v205, v0, v185
	v_mul_f32_e32 v206, v0, v198
	v_mul_f32_e32 v207, v0, v199
	v_cndmask_b32_e64 v179, v179, v203, s[0:1]
	v_cndmask_b32_e64 v180, v180, v202, s[0:1]
	v_cndmask_b32_e64 v152, v153, v201, s[0:1]
	v_cndmask_b32_e64 v153, v154, v200, s[0:1]
	v_cndmask_b32_e64 v155, v195, v207, s[0:1]
	v_cndmask_b32_e64 v171, v198, v206, s[0:1]
	v_cndmask_b32_e64 v173, v183, v205, s[0:1]
	v_cndmask_b32_e64 v177, v184, v204, s[0:1]
	v_cvt_pk_bf16_f32 v152, v153, v152
	v_cvt_pk_bf16_f32 v153, v180, v179
	v_mad_i64_i32 v[180:181], s[6:7], v176, s47, v[166:167]
	v_cvt_pk_bf16_f32 v154, v177, v173
	v_cvt_pk_bf16_f32 v155, v171, v155
	v_lshl_add_u64 v[180:181], v[180:181], 0, v[168:169]
	global_store_dwordx4 v[180:181], v[152:155], off
	s_nop 1
	v_mul_f32_e32 v152, v38, v127
	v_mul_f32_e32 v153, v39, v127
	v_mul_f32_e32 v171, v41, v170
	v_mul_f32_e32 v170, v40, v170
	v_mul_f32_e32 v184, v30, v123
	v_mul_f32_e32 v185, v31, v123
	v_mul_f32_e32 v179, v33, v178
	v_mul_f32_e32 v178, v32, v178
	v_fma_f32 v154, v38, v126, -v153
	v_fma_f32 v153, v39, v126, v152
	v_fma_f32 v182, v40, v128, -v171
	v_fma_f32 v171, v41, v128, v170
	v_fma_f32 v190, v30, v122, -v185
	v_fma_f32 v185, v31, v122, v184
	v_fma_f32 v186, v32, v124, -v179
	v_fma_f32 v179, v33, v124, v178
	v_mov_b32_e32 v155, v153
	v_mov_b32_e32 v183, v171
	v_mov_b32_e32 v191, v185
	v_mov_b32_e32 v187, v179
	v_mul_f32_e32 v188, v0, v154
	v_mul_f32_e32 v189, v0, v155
	v_mul_f32_e32 v192, v0, v182
	v_mul_f32_e32 v193, v0, v183
	v_mul_f32_e32 v194, v0, v190
	v_mul_f32_e32 v195, v0, v191
	v_mul_f32_e32 v198, v0, v186
	v_mul_f32_e32 v199, v0, v187
	v_cndmask_b32_e32 v0, v179, v199, vcc
	v_cndmask_b32_e32 v155, v186, v198, vcc
	v_cndmask_b32_e32 v170, v185, v195, vcc
	v_cndmask_b32_e32 v173, v190, v194, vcc
	v_cndmask_b32_e32 v171, v171, v193, vcc
	v_cndmask_b32_e32 v177, v182, v192, vcc
	v_cndmask_b32_e32 v152, v153, v189, vcc
	v_cndmask_b32_e32 v153, v154, v188, vcc
	v_cvt_pk_bf16_f32 v152, v153, v152
	v_cvt_pk_bf16_f32 v153, v177, v171
	v_cvt_pk_bf16_f32 v154, v173, v170
	v_cvt_pk_bf16_f32 v155, v155, v0
	global_store_dwordx4 v[180:181], v[152:155], off offset:256
	v_mov_b32_e32 v170, v113
	v_mul_f32_e32 v178, v36, v170
	v_mul_f32_e32 v179, v37, v170
	v_mul_f32_e32 v152, v34, v111
	v_mul_f32_e32 v153, v35, v111
	v_fma_f32 v180, v36, v112, -v179
	v_fma_f32 v179, v37, v112, v178
	v_mul_f32_e32 v182, v26, v107
	v_mul_f32_e32 v183, v27, v107
	v_mov_b32_e32 v178, v109
	v_mul_f32_e32 v186, v28, v178
	v_mul_f32_e32 v187, v29, v178
	v_cmp_lt_i32_e64 s[38:39], s11, v238
	v_fma_f32 v154, v34, v110, -v153
	v_fma_f32 v153, v35, v110, v152
	v_fma_f32 v184, v26, v106, -v183
	v_fma_f32 v183, v27, v106, v182
	v_fma_f32 v188, v28, v108, -v187
	v_fma_f32 v187, v29, v108, v186
	v_cndmask_b32_e64 v0, 0, v231, s[38:39]
	v_mov_b32_e32 v155, v153
	v_mov_b32_e32 v181, v179
	v_mov_b32_e32 v185, v183
	v_mov_b32_e32 v189, v187
	v_mul_f32_e32 v190, v0, v154
	v_mul_f32_e32 v191, v0, v155
	v_mul_f32_e32 v192, v0, v180
	v_mul_f32_e32 v193, v0, v181
	v_mul_f32_e32 v194, v0, v184
	v_mul_f32_e32 v195, v0, v185
	v_mul_f32_e32 v196, v0, v188
	v_mul_f32_e32 v197, v0, v189
	v_cndmask_b32_e64 v141, v187, v197, s[0:1]
	v_cndmask_b32_e64 v145, v188, v196, s[0:1]
	v_cndmask_b32_e64 v155, v183, v195, s[0:1]
	v_cndmask_b32_e64 v171, v184, v194, s[0:1]
	v_cndmask_b32_e64 v173, v179, v193, s[0:1]
	v_cndmask_b32_e64 v177, v180, v192, s[0:1]
	v_cndmask_b32_e64 v152, v153, v191, s[0:1]
	v_cndmask_b32_e64 v153, v154, v190, s[0:1]
	v_mad_i64_i32 v[180:181], s[6:7], v233, s47, v[166:167]
	v_cvt_pk_bf16_f32 v152, v153, v152
	v_cvt_pk_bf16_f32 v153, v177, v173
	v_cvt_pk_bf16_f32 v154, v171, v155
	v_cvt_pk_bf16_f32 v155, v145, v141
	v_lshl_add_u64 v[180:181], v[180:181], 0, v[168:169]
	global_store_dwordx4 v[180:181], v[152:155], off
	s_nop 1
	v_mul_f32_e32 v152, v22, v111
	v_mul_f32_e32 v153, v23, v111
	s_nop 0
	v_fma_f32 v154, v22, v110, -v153
	v_fma_f32 v143, v23, v110, v152
	v_mul_f32_e32 v152, v24, v170
	v_mul_f32_e32 v153, v25, v170
	v_mov_b32_e32 v155, v143
	v_fma_f32 v170, v24, v112, -v153
	v_fma_f32 v145, v25, v112, v152
	v_mul_f32_e32 v152, v14, v107
	v_mul_f32_e32 v153, v15, v107
	v_mov_b32_e32 v171, v145
	v_fma_f32 v182, v14, v106, -v153
	v_fma_f32 v139, v15, v106, v152
	v_mul_f32_e32 v152, v16, v178
	v_mul_f32_e32 v153, v17, v178
	v_mov_b32_e32 v183, v139
	v_fma_f32 v178, v16, v108, -v153
	v_fma_f32 v141, v17, v108, v152
	v_mul_f32_e32 v152, v0, v154
	v_mul_f32_e32 v153, v0, v155
	v_mov_b32_e32 v179, v141
	v_mul_f32_e32 v184, v0, v170
	v_mul_f32_e32 v185, v0, v171
	v_mul_f32_e32 v186, v0, v182
	v_mul_f32_e32 v187, v0, v183
	v_mul_f32_e32 v188, v0, v178
	v_mul_f32_e32 v189, v0, v179
	v_cndmask_b32_e32 v0, v141, v189, vcc
	v_cndmask_b32_e32 v141, v178, v188, vcc
	v_cndmask_b32_e32 v140, v139, v187, vcc
	v_cndmask_b32_e32 v142, v182, v186, vcc
	v_cndmask_b32_e32 v139, v145, v185, vcc
	v_cndmask_b32_e32 v144, v170, v184, vcc
	v_cndmask_b32_e32 v138, v143, v153, vcc
	v_cndmask_b32_e32 v143, v154, v152, vcc
	v_cvt_pk_bf16_f32 v138, v143, v138
	v_cvt_pk_bf16_f32 v139, v144, v139
	v_cvt_pk_bf16_f32 v140, v142, v140
	v_cvt_pk_bf16_f32 v141, v141, v0
	global_store_dwordx4 v[180:181], v[138:141], off offset:256
	v_mov_b32_e32 v142, v105
	v_mul_f32_e32 v144, v20, v142
	v_mul_f32_e32 v145, v21, v142
	v_mul_f32_e32 v138, v18, v103
	v_mul_f32_e32 v139, v19, v103
	v_fma_f32 v152, v20, v104, -v145
	v_fma_f32 v145, v21, v104, v144
	v_cmp_lt_i32_e64 s[38:39], s11, v226
	v_mov_b32_e32 v144, v97
	v_fma_f32 v140, v18, v102, -v139
	v_fma_f32 v139, v19, v102, v138
	v_mul_f32_e32 v154, v10, v95
	v_mul_f32_e32 v155, v11, v95
	v_mul_f32_e32 v172, v12, v144
	v_mul_f32_e32 v173, v13, v144
	v_cndmask_b32_e64 v0, 0, v231, s[38:39]
	v_fma_f32 v170, v10, v94, -v155
	v_fma_f32 v155, v11, v94, v154
	v_fma_f32 v178, v12, v96, -v173
	v_fma_f32 v215, v12, v96, v173
	v_fma_f32 v173, v13, v96, v172
	v_mov_b32_e32 v172, v215
	v_mov_b32_e32 v141, v139
	v_mov_b32_e32 v153, v145
	v_mul_f32_e32 v180, v0, v140
	v_mul_f32_e32 v181, v0, v141
	v_mul_f32_e32 v182, v0, v152
	v_mul_f32_e32 v183, v0, v153
	v_mov_b32_e32 v171, v155
	v_mov_b32_e32 v179, v173
	v_mul_f32_e32 v184, v0, v170
	v_mul_f32_e32 v185, v0, v171
	v_mul_f32_e32 v186, v0, v178
	v_mul_f32_e32 v187, v0, v179
	v_cndmask_b32_e64 v145, v145, v183, s[0:1]
	v_cndmask_b32_e64 v152, v152, v182, s[0:1]
	v_cndmask_b32_e64 v138, v139, v181, s[0:1]
	v_cndmask_b32_e64 v139, v140, v180, s[0:1]
	v_cndmask_b32_e64 v133, v173, v187, s[0:1]
	v_cndmask_b32_e64 v137, v178, v186, s[0:1]
	v_cndmask_b32_e64 v141, v155, v185, s[0:1]
	v_cndmask_b32_e64 v143, v170, v184, s[0:1]
	v_cvt_pk_bf16_f32 v138, v139, v138
	v_cvt_pk_bf16_f32 v139, v152, v145
	v_mad_i64_i32 v[152:153], s[0:1], v252, s47, v[166:167]
	v_cvt_pk_bf16_f32 v140, v143, v141
	v_cvt_pk_bf16_f32 v141, v137, v133
	v_lshl_add_u64 v[152:153], v[152:153], 0, v[168:169]
	global_store_dwordx4 v[152:153], v[138:141], off
	s_nop 1
	v_mul_f32_e32 v138, v6, v103
	v_mul_f32_e32 v139, v7, v103
	s_nop 0
	v_fma_f32 v140, v6, v102, -v139
	v_fma_f32 v135, v7, v102, v138
	v_mul_f32_e32 v138, v8, v142
	v_mul_f32_e32 v139, v9, v142
	v_mov_b32_e32 v141, v135
	v_fma_f32 v142, v8, v104, -v139
	v_fma_f32 v137, v9, v104, v138
	v_mul_f32_e32 v138, v2, v95
	v_mul_f32_e32 v139, v3, v95
	v_mov_b32_e32 v143, v137
	v_fma_f32 v154, v2, v94, -v139
	v_fma_f32 v131, v3, v94, v138
	v_mul_f32_e32 v138, v4, v144
	v_mul_f32_e32 v139, v5, v144
	v_mov_b32_e32 v155, v131
	v_fma_f32 v144, v4, v96, -v139
	v_fma_f32 v133, v5, v96, v138
	v_mul_f32_e32 v138, v0, v140
	v_mul_f32_e32 v139, v0, v141
	v_mov_b32_e32 v145, v133
	v_mul_f32_e32 v166, v0, v142
	v_mul_f32_e32 v167, v0, v143
	v_mul_f32_e32 v168, v0, v154
	v_mul_f32_e32 v169, v0, v155
	v_mul_f32_e32 v170, v0, v144
	v_mul_f32_e32 v171, v0, v145
	v_cndmask_b32_e32 v0, v133, v171, vcc
	v_cndmask_b32_e32 v133, v144, v170, vcc
	v_cndmask_b32_e32 v132, v131, v169, vcc
	v_cndmask_b32_e32 v134, v154, v168, vcc
	v_cndmask_b32_e32 v131, v137, v167, vcc
	v_cndmask_b32_e32 v136, v142, v166, vcc
	v_cndmask_b32_e32 v130, v135, v139, vcc
	v_cndmask_b32_e32 v135, v140, v138, vcc
	v_cvt_pk_bf16_f32 v130, v135, v130
	v_cvt_pk_bf16_f32 v131, v136, v131
	v_cvt_pk_bf16_f32 v132, v134, v132
	v_cvt_pk_bf16_f32 v133, v133, v0
	global_store_dwordx4 v[152:153], v[130:133], off offset:256

.LBB0_157:
	s_andn2_b64 vcc, exec, s[0:1]
	s_cbranch_vccnz .LBB0_128
	s_lshr_b32 s0, s75, 3
	s_mulk_i32 s0, 0x880
	s_lshl_b32 s1, s75, 8
	s_and_b32 s1, s1, 0x700
	s_add_i32 s0, s0, s66
	s_add_i32 s0, s0, s1
	v_or_b32_e32 v196, s0, v176
	s_lshl_b32 s0, s69, 8
	v_lshl_or_b32 v0, v175, 3, s0
	v_or_b32_e32 v144, s61, v0
	s_nop 0
	v_and_b32_e32 v0, 62, v144
	v_lshlrev_b32_e32 v0, 2, v0
	v_lshl_add_u64 v[130:131], s[28:29], 0, v[0:1]
	v_mul_hi_i32 v0, v196, s63
	v_lshrrev_b32_e32 v132, 31, v0
	v_ashrrev_i32_e32 v0, 10, v0
	v_add_u32_e32 v0, v0, v132
	v_mul_i32_i24_e32 v0, 0x880, v0
	v_add_u32_e32 v175, 16, v196
	v_sub_u32_e32 v132, v196, v0
	v_mul_hi_i32 v0, v175, s63
	v_lshrrev_b32_e32 v140, 31, v0
	v_ashrrev_i32_e32 v0, 10, v0
	v_add_u32_e32 v0, v0, v140
	v_mul_i32_i24_e32 v0, 0x880, v0
	v_add_u32_e32 v197, 32, v196
	v_sub_u32_e32 v140, v175, v0
	v_mul_hi_i32 v0, v197, s63
	v_lshrrev_b32_e32 v145, 31, v0
	v_ashrrev_i32_e32 v0, 10, v0
	v_add_u32_e32 v0, v0, v145
	v_mul_i32_i24_e32 v0, 0x880, v0
	v_add_u32_e32 v198, 48, v196
	v_sub_u32_e32 v166, v197, v0
	v_mul_hi_i32 v0, v198, s63
	v_lshrrev_b32_e32 v145, 31, v0
	v_ashrrev_i32_e32 v0, 10, v0
	v_add_u32_e32 v0, v0, v145
	v_mul_i32_i24_e32 v0, 0x880, v0
	v_sub_u32_e32 v176, v198, v0
	v_ashrrev_i32_e32 v133, 31, v132
	v_ashrrev_i32_e32 v141, 31, v140
	v_ashrrev_i32_e32 v167, 31, v166
	v_ashrrev_i32_e32 v177, 31, v176
	v_lshlrev_b64 v[132:133], 8, v[132:133]
	v_lshlrev_b64 v[140:141], 8, v[140:141]
	v_lshlrev_b64 v[166:167], 8, v[166:167]
	v_lshlrev_b64 v[176:177], 8, v[176:177]
	v_lshl_add_u64 v[136:137], v[130:131], 0, v[132:133]
	v_lshl_add_u64 v[152:153], v[130:131], 0, v[140:141]
	v_lshl_add_u64 v[170:171], v[130:131], 0, v[166:167]
	v_lshl_add_u64 v[180:181], v[130:131], 0, v[176:177]
	global_load_dwordx4 v[132:135], v[136:137], off offset:16
	s_nop 0
	global_load_dwordx4 v[136:139], v[136:137], off
	s_nop 0
	global_load_dwordx4 v[140:143], v[152:153], off offset:16
	s_nop 0
	global_load_dwordx4 v[152:155], v[152:153], off
	s_nop 0
	global_load_dwordx4 v[166:169], v[170:171], off offset:16
	s_nop 0
	global_load_dwordx4 v[170:173], v[170:171], off
	s_nop 0
	global_load_dwordx4 v[176:179], v[180:181], off offset:16
	s_nop 0
	global_load_dwordx4 v[180:183], v[180:181], off
	s_waitcnt vmcnt(0)
	v_mul_f32_e32 v184, v126, v137
	v_mul_f32_e32 v185, v127, v137
	v_mov_b32_e32 v0, v139
	v_fma_f32 v186, v126, v136, -v185
	v_fma_f32 v127, v127, v136, v184
	v_mul_f32_e32 v184, v128, v0
	v_mul_f32_e32 v185, v129, v0
	v_ashrrev_i32_e32 v145, 31, v144
	v_fma_f32 v188, v128, v138, -v185
	v_fma_f32 v189, v129, v139, -v184
	v_fma_f32 v129, v129, v138, v184
	v_mul_f32_e32 v184, v122, v133
	v_mul_f32_e32 v185, v123, v133
	v_cvt_pk_bf16_f32 v126, v186, v127
	v_fma_f32 v190, v122, v132, -v185
	v_fma_f32 v191, v123, v133, -v184
	v_fma_f32 v123, v123, v132, v184
	v_mov_b32_e32 v184, v135
	v_mul_f32_e32 v192, v124, v184
	v_mul_f32_e32 v193, v125, v184
	v_cvt_pk_bf16_f32 v128, v190, v123
	v_fma_f32 v194, v124, v134, -v193
	v_fma_f32 v195, v125, v135, -v192
	v_fma_f32 v125, v125, v134, v192
	v_mov_b64_e32 v[122:123], s[8:9]
	v_cvt_pk_bf16_f32 v127, v188, v129
	v_cvt_pk_bf16_f32 v129, v194, v125
	v_mad_i64_i32 v[186:187], s[0:1], v196, s47, v[122:123]
	v_lshlrev_b64 v[124:125], 1, v[144:145]
	v_lshl_add_u64 v[144:145], v[186:187], 0, v[124:125]
	global_store_dwordx4 v[144:145], v[126:129], off
	s_nop 1
	v_mul_f32_e32 v126, v118, v137
	v_mul_f32_e32 v127, v119, v137
	s_nop 0
	v_fma_f32 v128, v118, v136, -v127
	v_fma_f32 v119, v119, v136, v126
	v_mul_f32_e32 v126, v120, v0
	v_mul_f32_e32 v127, v121, v0
	s_nop 0
	v_fma_f32 v136, v120, v138, -v127
	v_fma_f32 v121, v121, v138, v126
	v_mul_f32_e32 v126, v110, v133
	v_mul_f32_e32 v127, v111, v133
	s_nop 0
	v_fma_f32 v138, v110, v132, -v127
	v_fma_f32 v127, v111, v132, v126
	v_mul_f32_e32 v110, v112, v184
	v_mul_f32_e32 v111, v113, v184
	s_nop 0
	v_fma_f32 v132, v112, v134, -v111
	v_fma_f32 v113, v113, v134, v110
	v_cvt_pk_bf16_f32 v110, v128, v119
	v_cvt_pk_bf16_f32 v111, v136, v121
	v_cvt_pk_bf16_f32 v112, v138, v127
	v_cvt_pk_bf16_f32 v113, v132, v113
	global_store_dwordx4 v[144:145], v[110:113], off offset:256
	s_nop 1
	v_mul_f32_e32 v110, v114, v153
	v_mul_f32_e32 v111, v115, v153
	v_mov_b32_e32 v0, v155
	v_fma_f32 v112, v114, v152, -v111
	v_fma_f32 v111, v115, v152, v110
	v_mul_f32_e32 v114, v116, v0
	v_mul_f32_e32 v115, v117, v0
	v_mov_b32_e32 v110, v143
	v_fma_f32 v118, v116, v154, -v115
	v_fma_f32 v115, v117, v154, v114
	v_mul_f32_e32 v116, v106, v141
	v_mul_f32_e32 v117, v107, v141
	s_nop 0
	v_fma_f32 v120, v106, v140, -v117
	v_fma_f32 v121, v107, v141, -v116
	v_fma_f32 v117, v107, v140, v116
	v_mul_f32_e32 v106, v108, v110
	v_mul_f32_e32 v107, v109, v110
	s_nop 0
	v_fma_f32 v126, v108, v142, -v107
	v_fma_f32 v109, v109, v142, v106
	v_cvt_pk_bf16_f32 v106, v112, v111
	v_mad_i64_i32 v[112:113], s[0:1], v175, s47, v[122:123]
	v_cvt_pk_bf16_f32 v107, v118, v115
	v_cvt_pk_bf16_f32 v108, v120, v117
	v_cvt_pk_bf16_f32 v109, v126, v109
	v_lshl_add_u64 v[112:113], v[112:113], 0, v[124:125]
	global_store_dwordx4 v[112:113], v[106:109], off
	s_nop 1
	v_mul_f32_e32 v106, v102, v153
	v_mul_f32_e32 v107, v103, v153
	s_nop 0
	v_fma_f32 v108, v102, v152, -v107
	v_fma_f32 v109, v103, v153, -v106
	v_fma_f32 v103, v103, v152, v106
	v_mul_f32_e32 v106, v104, v0
	v_mul_f32_e32 v107, v105, v0
	s_nop 0
	v_fma_f32 v114, v104, v154, -v107
	v_fma_f32 v105, v105, v154, v106
	v_mul_f32_e32 v106, v94, v141
	v_mul_f32_e32 v107, v95, v141
	s_nop 0
	v_fma_f32 v116, v94, v140, -v107
	v_fma_f32 v107, v95, v140, v106
	v_mul_f32_e32 v94, v96, v110
	v_mul_f32_e32 v95, v97, v110
	s_nop 0
	v_fma_f32 v110, v96, v142, -v95
	v_fma_f32 v111, v97, v143, -v94
	v_fma_f32 v97, v97, v142, v94
	v_cvt_pk_bf16_f32 v94, v108, v103
	v_cvt_pk_bf16_f32 v95, v114, v105
	v_cvt_pk_bf16_f32 v96, v116, v107
	v_cvt_pk_bf16_f32 v97, v110, v97
	global_store_dwordx4 v[112:113], v[94:97], off offset:256
	s_nop 1
	v_add_u32_e32 v147, 0x80, v196
	v_mul_hi_i32 v0, v147, s63
	v_lshrrev_b32_e32 v112, 31, v0
	v_ashrrev_i32_e32 v0, 10, v0
	v_add_u32_e32 v0, v0, v112
	v_mul_i32_i24_e32 v0, 0x880, v0
	v_add_u32_e32 v199, 0x90, v196
	v_sub_u32_e32 v112, v147, v0
	v_mul_hi_i32 v0, v199, s63
	v_lshrrev_b32_e32 v126, 31, v0
	v_ashrrev_i32_e32 v0, 10, v0
	v_add_u32_e32 v0, v0, v126
	v_mul_i32_i24_e32 v0, 0x880, v0
	v_add_u32_e32 v211, 0xa0, v196
	v_sub_u32_e32 v126, v199, v0
	v_mul_hi_i32 v0, v211, s63
	v_lshrrev_b32_e32 v136, 31, v0
	v_ashrrev_i32_e32 v0, 10, v0
	v_add_u32_e32 v0, v0, v136
	v_mul_i32_i24_e32 v0, 0x880, v0
	v_add_u32_e32 v215, 0xb0, v196
	v_sub_u32_e32 v136, v211, v0
	v_mul_hi_i32 v0, v215, s63
	v_lshrrev_b32_e32 v152, 31, v0
	v_ashrrev_i32_e32 v0, 10, v0
	v_add_u32_e32 v0, v0, v152
	v_mul_i32_i24_e32 v0, 0x880, v0
	v_sub_u32_e32 v152, v215, v0
	v_ashrrev_i32_e32 v113, 31, v112
	v_ashrrev_i32_e32 v127, 31, v126
	v_ashrrev_i32_e32 v137, 31, v136
	v_ashrrev_i32_e32 v153, 31, v152
	v_lshlrev_b64 v[112:113], 8, v[112:113]
	v_lshlrev_b64 v[126:127], 8, v[126:127]
	v_lshlrev_b64 v[136:137], 8, v[136:137]
	v_lshlrev_b64 v[152:153], 8, v[152:153]
	v_lshl_add_u64 v[116:117], v[130:131], 0, v[112:113]
	v_lshl_add_u64 v[132:133], v[130:131], 0, v[126:127]
	v_lshl_add_u64 v[140:141], v[130:131], 0, v[136:137]
	v_lshl_add_u64 v[184:185], v[130:131], 0, v[152:153]
	global_load_dwordx4 v[112:115], v[116:117], off offset:16
	s_nop 0
	global_load_dwordx4 v[116:119], v[116:117], off
	s_nop 0
	global_load_dwordx4 v[126:129], v[132:133], off offset:16
	s_nop 0
	global_load_dwordx4 v[132:135], v[132:133], off
	s_nop 0
	global_load_dwordx4 v[136:139], v[140:141], off offset:16
	s_nop 0
	global_load_dwordx4 v[140:143], v[140:141], off
	s_nop 0
	global_load_dwordx4 v[152:155], v[184:185], off offset:16
	s_nop 0
	global_load_dwordx4 v[184:187], v[184:185], off
	s_nop 1
	v_mul_f32_e32 v94, v98, v171
	v_mul_f32_e32 v95, v99, v171
	v_mov_b32_e32 v0, v173
	v_fma_f32 v96, v98, v170, -v95
	v_fma_f32 v95, v99, v170, v94
	v_mul_f32_e32 v98, v100, v0
	v_mul_f32_e32 v99, v101, v0
	v_mov_b32_e32 v94, v169
	v_fma_f32 v102, v100, v172, -v99
	v_fma_f32 v99, v101, v172, v98
	v_mul_f32_e32 v100, v90, v167
	v_mul_f32_e32 v101, v91, v167
	s_nop 0
	v_fma_f32 v104, v90, v166, -v101
	v_fma_f32 v101, v91, v166, v100
	v_mul_f32_e32 v90, v92, v94
	v_mul_f32_e32 v91, v93, v94
	s_nop 0
	v_fma_f32 v106, v92, v168, -v91
	v_fma_f32 v93, v93, v168, v90
	v_cvt_pk_bf16_f32 v90, v96, v95
	v_mad_i64_i32 v[96:97], s[0:1], v197, s47, v[122:123]
	v_cvt_pk_bf16_f32 v91, v102, v99
	v_cvt_pk_bf16_f32 v92, v104, v101
	v_cvt_pk_bf16_f32 v93, v106, v93
	v_lshl_add_u64 v[96:97], v[96:97], 0, v[124:125]
	global_store_dwordx4 v[96:97], v[90:93], off
	s_nop 1
	v_mul_f32_e32 v90, v86, v171
	v_mul_f32_e32 v91, v87, v171
	s_nop 0
	v_fma_f32 v92, v86, v170, -v91
	v_fma_f32 v93, v87, v171, -v90
	v_fma_f32 v87, v87, v170, v90
	v_mul_f32_e32 v90, v88, v0
	v_mul_f32_e32 v91, v89, v0
	s_nop 0
	v_fma_f32 v98, v88, v172, -v91
	v_fma_f32 v89, v89, v172, v90
	v_mul_f32_e32 v90, v78, v167
	v_mul_f32_e32 v91, v79, v167
	s_nop 0
	v_fma_f32 v100, v78, v166, -v91
	v_fma_f32 v91, v79, v166, v90
	v_mul_f32_e32 v78, v80, v94
	v_mul_f32_e32 v79, v81, v94
	s_nop 0
	v_fma_f32 v94, v80, v168, -v79
	v_fma_f32 v95, v81, v169, -v78
	v_fma_f32 v81, v81, v168, v78
	v_cvt_pk_bf16_f32 v78, v92, v87
	v_cvt_pk_bf16_f32 v79, v98, v89
	v_cvt_pk_bf16_f32 v80, v100, v91
	v_cvt_pk_bf16_f32 v81, v94, v81
	global_store_dwordx4 v[96:97], v[78:81], off offset:256
	s_nop 1
	v_mul_f32_e32 v78, v82, v181
	v_mul_f32_e32 v79, v83, v181
	v_mov_b32_e32 v0, v183
	v_fma_f32 v80, v82, v180, -v79
	v_fma_f32 v79, v83, v180, v78
	v_mul_f32_e32 v82, v84, v0
	v_mul_f32_e32 v83, v85, v0
	v_mov_b32_e32 v78, v179
	v_fma_f32 v86, v84, v182, -v83
	v_fma_f32 v87, v85, v183, -v82
	v_fma_f32 v83, v85, v182, v82
	v_mul_f32_e32 v84, v74, v177
	v_mul_f32_e32 v85, v75, v177
	s_nop 0
	v_fma_f32 v88, v74, v176, -v85
	v_fma_f32 v89, v75, v177, -v84
	v_fma_f32 v85, v75, v176, v84
	v_mul_f32_e32 v74, v76, v78
	v_mul_f32_e32 v75, v77, v78
	s_nop 0
	v_fma_f32 v90, v76, v178, -v75
	v_fma_f32 v91, v77, v179, -v74
	v_fma_f32 v77, v77, v178, v74
	v_cvt_pk_bf16_f32 v74, v80, v79
	v_mad_i64_i32 v[80:81], s[0:1], v198, s47, v[122:123]
	v_cvt_pk_bf16_f32 v75, v86, v83
	v_cvt_pk_bf16_f32 v76, v88, v85
	v_cvt_pk_bf16_f32 v77, v90, v77
	v_lshl_add_u64 v[80:81], v[80:81], 0, v[124:125]
	global_store_dwordx4 v[80:81], v[74:77], off
	s_nop 1
	v_mul_f32_e32 v74, v70, v181
	v_mul_f32_e32 v75, v71, v181
	s_nop 0
	v_fma_f32 v76, v70, v180, -v75
	v_fma_f32 v77, v71, v181, -v74
	v_fma_f32 v71, v71, v180, v74
	v_mul_f32_e32 v74, v72, v0
	v_mul_f32_e32 v75, v73, v0
	s_nop 0
	v_fma_f32 v82, v72, v182, -v75
	v_fma_f32 v83, v73, v183, -v74
	v_fma_f32 v73, v73, v182, v74
	v_mul_f32_e32 v74, v66, v177
	v_mul_f32_e32 v75, v67, v177
	s_nop 0
	v_fma_f32 v84, v66, v176, -v75
	v_fma_f32 v85, v67, v177, -v74
	v_fma_f32 v212, v66, v176, v75
	v_fma_f32 v75, v67, v176, v74
	v_mov_b32_e32 v74, v212
	v_mul_f32_e32 v66, v68, v78
	v_mul_f32_e32 v67, v69, v78
	s_nop 0
	v_fma_f32 v78, v68, v178, -v67
	v_fma_f32 v79, v69, v179, -v66
	v_fma_f32 v69, v69, v178, v66
	v_cvt_pk_bf16_f32 v66, v76, v71
	v_cvt_pk_bf16_f32 v67, v82, v73
	v_cvt_pk_bf16_f32 v68, v84, v75
	v_cvt_pk_bf16_f32 v69, v78, v69
	global_store_dwordx4 v[80:81], v[66:69], off offset:256
	s_waitcnt vmcnt(4)
	v_mul_f32_e32 v98, v62, v117
	v_mul_f32_e32 v99, v63, v117
	v_mov_b32_e32 v0, v119
	v_fma_f32 v100, v62, v116, -v99
	v_fma_f32 v101, v63, v117, -v98
	v_fma_f32 v63, v63, v116, v98
	v_mul_f32_e32 v98, v64, v0
	v_mul_f32_e32 v99, v65, v0
	v_mov_b32_e32 v62, v115
	v_fma_f32 v102, v64, v118, -v99
	v_fma_f32 v103, v65, v119, -v98
	v_fma_f32 v65, v65, v118, v98
	v_mul_f32_e32 v98, v58, v113
	v_mul_f32_e32 v99, v59, v113
	s_nop 0
	v_fma_f32 v104, v58, v112, -v99
	v_fma_f32 v105, v59, v113, -v98
	v_fma_f32 v212, v58, v112, v99
	v_fma_f32 v99, v59, v112, v98
	v_mov_b32_e32 v98, v212
	v_mul_f32_e32 v58, v60, v62
	v_mul_f32_e32 v59, v61, v62
	s_nop 0
	v_fma_f32 v106, v60, v114, -v59
	v_fma_f32 v107, v61, v115, -v58
	v_fma_f32 v61, v61, v114, v58
	v_cvt_pk_bf16_f32 v59, v102, v65
	v_mad_i64_i32 v[64:65], s[0:1], v147, s47, v[122:123]
	v_cvt_pk_bf16_f32 v58, v100, v63
	v_cvt_pk_bf16_f32 v60, v104, v99
	v_cvt_pk_bf16_f32 v61, v106, v61
	v_lshl_add_u64 v[64:65], v[64:65], 0, v[124:125]
	global_store_dwordx4 v[64:65], v[58:61], off
	s_nop 1
	v_mul_f32_e32 v58, v54, v117
	v_mul_f32_e32 v59, v55, v117
	s_nop 0
	v_fma_f32 v60, v54, v116, -v59
	v_fma_f32 v61, v55, v117, -v58
	v_fma_f32 v55, v55, v116, v58
	v_mul_f32_e32 v58, v56, v0
	v_mul_f32_e32 v59, v57, v0
	s_nop 0
	v_fma_f32 v70, v56, v118, -v59
	v_fma_f32 v71, v57, v119, -v58
	v_fma_f32 v57, v57, v118, v58
	v_mul_f32_e32 v58, v46, v113
	v_mul_f32_e32 v59, v47, v113
	s_nop 0
	v_fma_f32 v72, v46, v112, -v59
	v_fma_f32 v73, v47, v113, -v58
	v_fma_f32 v59, v47, v112, v58
	v_mul_f32_e32 v46, v48, v62
	v_mul_f32_e32 v47, v49, v62
	s_nop 0
	v_fma_f32 v62, v48, v114, -v47
	v_fma_f32 v63, v49, v115, -v46
	v_fma_f32 v49, v49, v114, v46
	v_cvt_pk_bf16_f32 v46, v60, v55
	v_cvt_pk_bf16_f32 v47, v70, v57
	v_cvt_pk_bf16_f32 v48, v72, v59
	v_cvt_pk_bf16_f32 v49, v62, v49
	global_store_dwordx4 v[64:65], v[46:49], off offset:256
	s_nop 1
	v_mul_f32_e32 v46, v50, v133
	v_mul_f32_e32 v47, v51, v133
	v_mov_b32_e32 v0, v135
	v_fma_f32 v48, v50, v132, -v47
	v_fma_f32 v47, v51, v132, v46
	v_mul_f32_e32 v50, v52, v0
	v_mul_f32_e32 v51, v53, v0
	v_mov_b32_e32 v46, v129
	v_fma_f32 v54, v52, v134, -v51
	v_fma_f32 v55, v53, v135, -v50
	v_fma_f32 v51, v53, v134, v50
	v_mul_f32_e32 v52, v42, v127
	v_mul_f32_e32 v53, v43, v127
	s_nop 0
	v_fma_f32 v56, v42, v126, -v53
	v_fma_f32 v57, v43, v127, -v52
	v_fma_f32 v53, v43, v126, v52
	v_mul_f32_e32 v42, v44, v46
	v_mul_f32_e32 v43, v45, v46
	s_nop 0
	v_fma_f32 v58, v44, v128, -v43
	v_fma_f32 v59, v45, v129, -v42
	v_fma_f32 v45, v45, v128, v42
	v_cvt_pk_bf16_f32 v42, v48, v47
	v_mad_i64_i32 v[48:49], s[0:1], v199, s47, v[122:123]
	v_cvt_pk_bf16_f32 v43, v54, v51
	v_cvt_pk_bf16_f32 v44, v56, v53
	v_cvt_pk_bf16_f32 v45, v58, v45
	v_lshl_add_u64 v[48:49], v[48:49], 0, v[124:125]
	global_store_dwordx4 v[48:49], v[42:45], off
	s_nop 1
	v_mul_f32_e32 v42, v38, v133
	v_mul_f32_e32 v43, v39, v133
	s_nop 0
	v_fma_f32 v44, v38, v132, -v43
	v_fma_f32 v45, v39, v133, -v42
	v_fma_f32 v39, v39, v132, v42
	v_mul_f32_e32 v42, v40, v0
	v_mul_f32_e32 v43, v41, v0
	s_nop 0
	v_fma_f32 v50, v40, v134, -v43
	v_fma_f32 v51, v41, v135, -v42
	v_fma_f32 v41, v41, v134, v42
	v_mul_f32_e32 v42, v30, v127
	v_mul_f32_e32 v43, v31, v127
	s_nop 0
	v_fma_f32 v52, v30, v126, -v43
	v_fma_f32 v53, v31, v127, -v42
	v_fma_f32 v43, v31, v126, v42
	v_mul_f32_e32 v30, v32, v46
	v_mul_f32_e32 v31, v33, v46
	s_nop 0
	v_fma_f32 v46, v32, v128, -v31
	v_fma_f32 v47, v33, v129, -v30
	v_fma_f32 v33, v33, v128, v30
	v_cvt_pk_bf16_f32 v30, v44, v39
	v_cvt_pk_bf16_f32 v31, v50, v41
	v_cvt_pk_bf16_f32 v32, v52, v43
	v_cvt_pk_bf16_f32 v33, v46, v33
	global_store_dwordx4 v[48:49], v[30:33], off offset:256
	s_nop 1
	v_mul_f32_e32 v30, v34, v141
	v_mul_f32_e32 v31, v35, v141
	v_mov_b32_e32 v0, v143
	v_fma_f32 v32, v34, v140, -v31
	v_fma_f32 v31, v35, v140, v30
	v_mul_f32_e32 v34, v36, v0
	v_mul_f32_e32 v35, v37, v0
	v_mov_b32_e32 v30, v139
	v_fma_f32 v38, v36, v142, -v35
	v_fma_f32 v39, v37, v143, -v34
	v_fma_f32 v35, v37, v142, v34
	v_mul_f32_e32 v36, v26, v137
	v_mul_f32_e32 v37, v27, v137
	s_nop 0
	v_fma_f32 v40, v26, v136, -v37
	v_fma_f32 v41, v27, v137, -v36
	v_fma_f32 v37, v27, v136, v36
	v_mul_f32_e32 v26, v28, v30
	v_mul_f32_e32 v27, v29, v30
	s_nop 0
	v_fma_f32 v42, v28, v138, -v27
	v_fma_f32 v43, v29, v139, -v26
	v_fma_f32 v29, v29, v138, v26
	v_cvt_pk_bf16_f32 v26, v32, v31
	v_mad_i64_i32 v[32:33], s[0:1], v211, s47, v[122:123]
	v_cvt_pk_bf16_f32 v27, v38, v35
	v_cvt_pk_bf16_f32 v28, v40, v37
	v_cvt_pk_bf16_f32 v29, v42, v29
	v_lshl_add_u64 v[32:33], v[32:33], 0, v[124:125]
	global_store_dwordx4 v[32:33], v[26:29], off
	s_nop 1
	v_mul_f32_e32 v26, v22, v141
	v_mul_f32_e32 v27, v23, v141
	s_nop 0
	v_fma_f32 v28, v22, v140, -v27
	v_fma_f32 v29, v23, v141, -v26
	v_fma_f32 v23, v23, v140, v26
	v_mul_f32_e32 v26, v24, v0
	v_mul_f32_e32 v27, v25, v0
	s_nop 0
	v_fma_f32 v34, v24, v142, -v27
	v_fma_f32 v35, v25, v143, -v26
	v_fma_f32 v25, v25, v142, v26
	v_mul_f32_e32 v26, v14, v137
	v_mul_f32_e32 v27, v15, v137
	s_nop 0
	v_fma_f32 v36, v14, v136, -v27
	v_fma_f32 v37, v15, v137, -v26
	v_fma_f32 v27, v15, v136, v26
	v_mul_f32_e32 v14, v16, v30
	v_mul_f32_e32 v15, v17, v30
	s_nop 0
	v_fma_f32 v30, v16, v138, -v15
	v_fma_f32 v31, v17, v139, -v14
	v_fma_f32 v17, v17, v138, v14
	v_cvt_pk_bf16_f32 v14, v28, v23
	v_cvt_pk_bf16_f32 v15, v34, v25
	v_cvt_pk_bf16_f32 v16, v36, v27
	v_cvt_pk_bf16_f32 v17, v30, v17
	global_store_dwordx4 v[32:33], v[14:17], off offset:256
	s_nop 1
	v_mul_f32_e32 v14, v18, v185
	v_mul_f32_e32 v15, v19, v185
	v_mov_b32_e32 v0, v187
	v_fma_f32 v16, v18, v184, -v15
	v_fma_f32 v15, v19, v184, v14
	v_mul_f32_e32 v18, v20, v0
	v_mul_f32_e32 v19, v21, v0
	v_mov_b32_e32 v14, v155
	v_fma_f32 v22, v20, v186, -v19
	v_fma_f32 v23, v21, v187, -v18
	v_fma_f32 v19, v21, v186, v18
	v_mul_f32_e32 v20, v10, v153
	v_mul_f32_e32 v21, v11, v153
	s_nop 0
	v_fma_f32 v24, v10, v152, -v21
	v_fma_f32 v25, v11, v153, -v20
	v_fma_f32 v21, v11, v152, v20
	v_mul_f32_e32 v10, v12, v14
	v_mul_f32_e32 v11, v13, v14
	s_nop 0
	v_fma_f32 v26, v12, v154, -v11
	v_fma_f32 v27, v13, v155, -v10
	v_fma_f32 v13, v13, v154, v10
	v_cvt_pk_bf16_f32 v10, v16, v15
	v_mad_i64_i32 v[16:17], s[0:1], v215, s47, v[122:123]
	v_cvt_pk_bf16_f32 v11, v22, v19
	v_cvt_pk_bf16_f32 v12, v24, v21
	v_cvt_pk_bf16_f32 v13, v26, v13
	v_lshl_add_u64 v[16:17], v[16:17], 0, v[124:125]
	global_store_dwordx4 v[16:17], v[10:13], off
	s_nop 1
	v_mul_f32_e32 v10, v6, v185
	v_mul_f32_e32 v11, v7, v185
	s_nop 0
	v_fma_f32 v12, v6, v184, -v11
	v_fma_f32 v13, v7, v185, -v10
	v_fma_f32 v6, v6, v184, v11
	v_fma_f32 v7, v7, v184, v10
	v_mul_f32_e32 v10, v8, v0
	v_mul_f32_e32 v11, v9, v0
	s_nop 0
	v_fma_f32 v18, v8, v186, -v11
	v_fma_f32 v19, v9, v187, -v10
	v_fma_f32 v8, v8, v186, v11
	v_fma_f32 v9, v9, v186, v10
	v_mul_f32_e32 v10, v2, v153
	v_mul_f32_e32 v11, v3, v153
	s_nop 0
	v_fma_f32 v20, v2, v152, -v11
	v_fma_f32 v21, v3, v153, -v10
	v_fma_f32 v212, v2, v152, v11
	v_fma_f32 v11, v3, v152, v10
	v_mov_b32_e32 v10, v212
	v_mul_f32_e32 v2, v4, v14
	v_mul_f32_e32 v3, v5, v14
	s_nop 0
	v_fma_f32 v14, v4, v154, -v3
	v_fma_f32 v15, v5, v155, -v2
	v_fma_f32 v5, v5, v154, v2
	v_cvt_pk_bf16_f32 v2, v12, v7
	v_cvt_pk_bf16_f32 v3, v18, v9
	v_cvt_pk_bf16_f32 v4, v20, v11
	v_cvt_pk_bf16_f32 v5, v14, v5
	global_store_dwordx4 v[16:17], v[2:5], off offset:256
	s_branch .LBB0_128
